# grid barrier: per-workgroup census words read with ds_read_b32 instead of two serialized flat loads
# speedup vs baseline: 1.0018x; 1.0018x over previous
.LBB0_1174:
	s_add_i32 s12, 0, 0x23fc0
	s_cmp_lg_u32 s12, -1
	s_mov_b64 s[4:5], src_shared_base
	s_cselect_b32 s0, s12, 0
	s_cselect_b32 s4, s5, 0
	v_mov_b32_e32 v2, s0
	s_add_i32 s0, 0, 0x23fc4
	s_cmp_lg_u32 s0, -1
	v_mov_b32_e32 v3, s4
	s_cselect_b32 s4, s0, 0
	s_cselect_b32 s5, s5, 0
	s_waitcnt vmcnt(0) expcnt(0) lgkmcnt(0)
	v_mov_b32_e32 v6, s12
	v_mov_b32_e32 v4, s4
	v_mov_b32_e32 v5, s5
	ds_read_b32 v2, v6
	ds_read_b32 v0, v6 offset:4
	s_waitcnt lgkmcnt(0)
	v_cmp_eq_u32_e32 vcc, 0, v2
	s_and_saveexec_b64 s[4:5], vcc
	s_cbranch_execz .LBB0_1189
	s_mov_b32 s13, 1
	s_branch .LBB0_1177
